# speedup vs baseline: 1.0135x; 1.0006x over previous
; DEV int tid_opaque() { int t = threadIdx.x; asm volatile("" : "+v"(t)); return t; }
; DEV void wt_load(const WtDesc& d, float (&r)[16]) {
;     const int t = tid_opaque(), c = t & 63, r0 = t >> 6;
;     const int sc = c < 32 ? d.ca + c : d.cb + c - 32;
; #pragma unroll
;     for (int i = 0; i < 16; ++i) r[i] = d.src[(size_t)(r0 + 4 * i) * d.ld + sc];
; }
; DEV void wt_all(const Params& p, int bid, int nb, float* sm) {
;     int job = bid;
;     if (job >= 2 * WT_JOBS_L) return;
;     WtDesc d = wt_desc(p, job);
;     float r[16]; wt_load(d, r);
;     for (;;) {
;         const int nj = job + nb; const bool more = nj < 2 * WT_JOBS_L;
;         WtDesc dn = d; float rn[16];
;         if (more) { dn = wt_desc(p, nj); wt_load(dn, rn); }
;         wt_store(d, r, sm);
;         if (!more) break;
;         d = dn; job = nj;
; #pragma unroll
;         for (int i = 0; i < 16; ++i) r[i] = rn[i];
;     }
.LBB0_2673:
	v_mov_b32_e32 v1, v186
	s_sub_i32 s2, s13, 32
	v_and_b32_e32 v0, 63, v1
	v_mov_b32_e32 v2, s2
	v_mov_b32_e32 v3, s11
	v_cmp_gt_u32_e32 vcc, 32, v0
	v_ashrrev_i32_e32 v24, 6, v1
	s_mov_b32 s30, s78
	v_cndmask_b32_e32 v2, v2, v3, vcc
	v_add_u32_e32 v0, v2, v0
	v_ashrrev_i32_e32 v1, 31, v0
	v_lshl_add_u64 v[8:9], v[0:1], 2, s[4:5]
	v_ashrrev_i32_e32 v0, 31, v24
	v_mul_lo_u32 v2, s6, v0
	v_mul_lo_u32 v3, s7, v24
	v_mad_u64_u32 v[0:1], s[2:3], s6, v24, 0
	v_add3_u32 v1, v1, v2, v3
	v_add_u32_e32 v2, 4, v24
	v_ashrrev_i32_e32 v3, 31, v2
	v_mul_lo_u32 v4, s6, v3
	v_mul_lo_u32 v5, s7, v2
	v_mad_u64_u32 v[2:3], s[2:3], s6, v2, 0
	v_add3_u32 v3, v3, v4, v5
	v_add_u32_e32 v4, 8, v24
	v_ashrrev_i32_e32 v5, 31, v4
	v_mul_lo_u32 v6, s6, v5
	v_mul_lo_u32 v7, s7, v4
	v_mad_u64_u32 v[4:5], s[2:3], s6, v4, 0
	v_add3_u32 v5, v5, v6, v7
	v_add_u32_e32 v6, 12, v24
	v_ashrrev_i32_e32 v7, 31, v6
	v_mul_lo_u32 v10, s6, v7
	v_mul_lo_u32 v11, s7, v6
	v_mad_u64_u32 v[6:7], s[2:3], s6, v6, 0
	v_add3_u32 v7, v7, v10, v11
	v_add_u32_e32 v10, 16, v24
	v_ashrrev_i32_e32 v11, 31, v10
	v_mul_lo_u32 v12, s6, v11
	v_mul_lo_u32 v13, s7, v10
	v_mad_u64_u32 v[10:11], s[2:3], s6, v10, 0
	v_add3_u32 v11, v11, v12, v13
	v_add_u32_e32 v12, 20, v24
	v_ashrrev_i32_e32 v13, 31, v12
	v_mul_lo_u32 v14, s6, v13
	v_mul_lo_u32 v15, s7, v12
	v_mad_u64_u32 v[12:13], s[2:3], s6, v12, 0
	v_add3_u32 v13, v13, v14, v15
	v_add_u32_e32 v14, 24, v24
	v_ashrrev_i32_e32 v15, 31, v14
	v_mul_lo_u32 v16, s6, v15
	v_mul_lo_u32 v17, s7, v14
	v_mad_u64_u32 v[14:15], s[2:3], s6, v14, 0
	v_add3_u32 v15, v15, v16, v17
	v_add_u32_e32 v16, 28, v24
	v_ashrrev_i32_e32 v17, 31, v16
	v_mul_lo_u32 v18, s6, v17
	v_mul_lo_u32 v19, s7, v16
	v_mad_u64_u32 v[16:17], s[2:3], s6, v16, 0
	v_lshl_add_u64 v[0:1], v[0:1], 2, v[8:9]
	v_lshl_add_u64 v[2:3], v[2:3], 2, v[8:9]
	v_lshl_add_u64 v[4:5], v[4:5], 2, v[8:9]
	v_lshl_add_u64 v[6:7], v[6:7], 2, v[8:9]
	v_lshl_add_u64 v[10:11], v[10:11], 2, v[8:9]
	v_add3_u32 v17, v17, v18, v19
	v_lshl_add_u64 v[12:13], v[12:13], 2, v[8:9]
	v_lshl_add_u64 v[14:15], v[14:15], 2, v[8:9]
	v_lshl_add_u64 v[16:17], v[16:17], 2, v[8:9]
	global_load_dword v0, v[0:1], off
	s_nop 0
	global_load_dword v1, v[2:3], off
	s_nop 0
	global_load_dword v2, v[4:5], off
	global_load_dword v3, v[6:7], off
	s_nop 0
	global_load_dword v4, v[10:11], off
	global_load_dword v5, v[12:13], off
	global_load_dword v6, v[14:15], off
	global_load_dword v7, v[16:17], off
	v_add_u32_e32 v10, 32, v24
	v_ashrrev_i32_e32 v11, 31, v10
	v_mul_lo_u32 v12, s6, v11
	v_mul_lo_u32 v13, s7, v10
	v_mad_u64_u32 v[10:11], s[2:3], s6, v10, 0
	v_add3_u32 v11, v11, v12, v13
	v_add_u32_e32 v12, 36, v24
	v_ashrrev_i32_e32 v13, 31, v12
	v_mul_lo_u32 v14, s6, v13
	v_mul_lo_u32 v15, s7, v12
	v_mad_u64_u32 v[12:13], s[2:3], s6, v12, 0
	v_add3_u32 v13, v13, v14, v15
	v_add_u32_e32 v14, 40, v24
	v_ashrrev_i32_e32 v15, 31, v14
	v_mul_lo_u32 v16, s6, v15
	v_mul_lo_u32 v17, s7, v14
	v_mad_u64_u32 v[14:15], s[2:3], s6, v14, 0
	v_add3_u32 v15, v15, v16, v17
	v_add_u32_e32 v16, 44, v24
	v_ashrrev_i32_e32 v17, 31, v16
	v_mul_lo_u32 v18, s6, v17
	v_mul_lo_u32 v19, s7, v16
	v_mad_u64_u32 v[16:17], s[2:3], s6, v16, 0
	v_add3_u32 v17, v17, v18, v19
	v_add_u32_e32 v18, 48, v24
	v_ashrrev_i32_e32 v19, 31, v18
	v_mul_lo_u32 v20, s6, v19
	v_mul_lo_u32 v21, s7, v18
	v_mad_u64_u32 v[18:19], s[2:3], s6, v18, 0
	v_add3_u32 v19, v19, v20, v21
	v_add_u32_e32 v20, 52, v24
	v_ashrrev_i32_e32 v21, 31, v20
	v_mul_lo_u32 v22, s6, v21
	v_mul_lo_u32 v23, s7, v20
	v_mad_u64_u32 v[20:21], s[2:3], s6, v20, 0
	v_add3_u32 v21, v21, v22, v23
	v_add_u32_e32 v22, 56, v24
	v_ashrrev_i32_e32 v23, 31, v22
	v_mul_lo_u32 v25, s6, v23
	v_mul_lo_u32 v26, s7, v22
	v_mad_u64_u32 v[22:23], s[2:3], s6, v22, 0
	v_add_u32_e32 v24, 60, v24
	v_add3_u32 v23, v23, v25, v26
	v_ashrrev_i32_e32 v25, 31, v24
	v_mul_lo_u32 v26, s6, v25
	v_mul_lo_u32 v27, s7, v24
	v_mad_u64_u32 v[24:25], s[2:3], s6, v24, 0
	v_lshl_add_u64 v[10:11], v[10:11], 2, v[8:9]
	v_lshl_add_u64 v[12:13], v[12:13], 2, v[8:9]
	v_lshl_add_u64 v[14:15], v[14:15], 2, v[8:9]
	v_add3_u32 v25, v25, v26, v27
	v_lshl_add_u64 v[16:17], v[16:17], 2, v[8:9]
	v_lshl_add_u64 v[18:19], v[18:19], 2, v[8:9]
	v_lshl_add_u64 v[20:21], v[20:21], 2, v[8:9]
	v_lshl_add_u64 v[22:23], v[22:23], 2, v[8:9]
	v_lshl_add_u64 v[24:25], v[24:25], 2, v[8:9]
	global_load_dword v8, v[10:11], off
	global_load_dword v9, v[12:13], off
	s_nop 0
	global_load_dword v10, v[14:15], off
	global_load_dword v11, v[16:17], off
	global_load_dword v12, v[18:19], off
	global_load_dword v13, v[20:21], off
	s_nop 0
	global_load_dword v14, v[22:23], off
	global_load_dword v15, v[24:25], off
	v_readlane_b32 s2, v254, 1
	v_readlane_b32 s3, v254, 2
	s_add_u32 s13, s2, 0x3500000
	s_addc_u32 s14, s3, 0
	s_add_u32 s15, s2, 0x1f00000
	s_addc_u32 s16, s3, 0
	s_add_u32 s17, s2, 0x1b00000
	s_addc_u32 s18, s3, 0
	s_add_u32 s19, s2, 0x1a00000
	s_addc_u32 s20, s3, 0
	s_add_u32 s21, s2, 0x1880000
	s_addc_u32 s22, s3, 0
	s_add_u32 s23, s2, 0x1700000
	s_addc_u32 s28, s3, 0
	v_readlane_b32 s2, v254, 4
	v_readlane_b32 s3, v254, 5
	s_add_i32 s29, s78, s2
	v_mov_b32_e32 v16, 0
	v_mov_b32_e32 v17, 0
	v_mov_b32_e32 v18, 0
	v_mov_b32_e32 v19, 0
	v_mov_b32_e32 v20, 0
	v_mov_b32_e32 v21, 0
	v_mov_b32_e32 v22, 0
	v_mov_b32_e32 v23, 0
	v_mov_b32_e32 v24, 0
	v_mov_b32_e32 v25, 0
	v_mov_b32_e32 v26, 0
	v_mov_b32_e32 v27, 0
	v_mov_b32_e32 v28, 0
	v_mov_b32_e32 v29, 0
	v_mov_b32_e32 v30, 0
	v_mov_b32_e32 v31, 0
	s_mov_b64 s[2:3], s[0:1]
	s_mov_b32 s5, s12
	s_movk_i32 s4, 0x104
	s_branch .LBB0_2677
.Lwt_last:
	s_waitcnt vmcnt(0)
	s_branch .LBB0_2676

; DEV int tid_opaque() { int t = threadIdx.x; asm volatile("" : "+v"(t)); return t; }
; DEV void wt_load(const WtDesc& d, float (&r)[16]) {
;     const int t = tid_opaque(), c = t & 63, r0 = t >> 6;
;     const int sc = c < 32 ? d.ca + c : d.cb + c - 32;
; #pragma unroll
;     for (int i = 0; i < 16; ++i) r[i] = d.src[(size_t)(r0 + 4 * i) * d.ld + sc];
; }
; DEV void wt_all(const Params& p, int bid, int nb, float* sm) {
;     ...
;         const int nj = job + nb; const bool more = nj < 2 * WT_JOBS_L;
;         WtDesc dn = d; float rn[16];
;         if (more) { dn = wt_desc(p, nj); wt_load(dn, rn); }
.LBB0_2675:
	v_mov_b32_e32 v17, v186
	s_sub_i32 s4, s35, 32
	v_and_b32_e32 v16, 63, v17
	v_mov_b32_e32 v18, s4
	v_mov_b32_e32 v19, s34
	v_cmp_gt_u32_e32 vcc, 32, v16
	v_ashrrev_i32_e32 v32, 6, v17
	s_movk_i32 s4, 0x104
	v_cndmask_b32_e32 v18, v18, v19, vcc
	v_add_u32_e32 v16, v18, v16
	v_ashrrev_i32_e32 v17, 31, v16
	v_lshl_add_u64 v[24:25], v[16:17], 2, s[6:7]
	v_ashrrev_i32_e32 v16, 31, v32
	v_mul_lo_u32 v18, s8, v16
	v_mul_lo_u32 v19, s9, v32
	v_mad_u64_u32 v[16:17], s[6:7], s8, v32, 0
	v_add3_u32 v17, v17, v18, v19
	v_add_u32_e32 v18, 4, v32
	v_ashrrev_i32_e32 v19, 31, v18
	v_mul_lo_u32 v20, s8, v19
	v_mul_lo_u32 v21, s9, v18
	v_mad_u64_u32 v[18:19], s[6:7], s8, v18, 0
	v_add3_u32 v19, v19, v20, v21
	v_add_u32_e32 v20, 8, v32
	v_ashrrev_i32_e32 v21, 31, v20
	v_mul_lo_u32 v22, s8, v21
	v_mul_lo_u32 v23, s9, v20
	v_mad_u64_u32 v[20:21], s[6:7], s8, v20, 0
	v_add3_u32 v21, v21, v22, v23
	v_add_u32_e32 v22, 12, v32
	v_ashrrev_i32_e32 v23, 31, v22
	v_mul_lo_u32 v26, s8, v23
	v_mul_lo_u32 v27, s9, v22
	v_mad_u64_u32 v[22:23], s[6:7], s8, v22, 0
	v_add3_u32 v23, v23, v26, v27
	v_add_u32_e32 v26, 16, v32
	v_ashrrev_i32_e32 v27, 31, v26
	v_mul_lo_u32 v28, s8, v27
	v_mul_lo_u32 v29, s9, v26
	v_mad_u64_u32 v[26:27], s[6:7], s8, v26, 0
	v_add3_u32 v27, v27, v28, v29
	v_add_u32_e32 v28, 20, v32
	v_ashrrev_i32_e32 v29, 31, v28
	v_mul_lo_u32 v30, s8, v29
	v_mul_lo_u32 v31, s9, v28
	v_mad_u64_u32 v[28:29], s[6:7], s8, v28, 0
	v_add3_u32 v29, v29, v30, v31
	v_add_u32_e32 v30, 24, v32
	v_ashrrev_i32_e32 v31, 31, v30
	v_mul_lo_u32 v34, s8, v31
	v_mul_lo_u32 v35, s9, v30
	v_mad_u64_u32 v[30:31], s[6:7], s8, v30, 0
	v_add3_u32 v31, v31, v34, v35
	v_add_u32_e32 v34, 28, v32
	v_ashrrev_i32_e32 v35, 31, v34
	v_mul_lo_u32 v36, s8, v35
	v_mul_lo_u32 v37, s9, v34
	v_mad_u64_u32 v[34:35], s[6:7], s8, v34, 0
	v_lshl_add_u64 v[16:17], v[16:17], 2, v[24:25]
	v_lshl_add_u64 v[18:19], v[18:19], 2, v[24:25]
	v_lshl_add_u64 v[20:21], v[20:21], 2, v[24:25]
	v_lshl_add_u64 v[22:23], v[22:23], 2, v[24:25]
	v_lshl_add_u64 v[26:27], v[26:27], 2, v[24:25]
	v_add3_u32 v35, v35, v36, v37
	v_lshl_add_u64 v[28:29], v[28:29], 2, v[24:25]
	v_lshl_add_u64 v[30:31], v[30:31], 2, v[24:25]
	v_lshl_add_u64 v[34:35], v[34:35], 2, v[24:25]
	global_load_dword v16, v[16:17], off
	s_nop 0
	global_load_dword v17, v[18:19], off
	s_nop 0
	global_load_dword v18, v[20:21], off
	global_load_dword v19, v[22:23], off
	s_nop 0
	global_load_dword v20, v[26:27], off
	global_load_dword v21, v[28:29], off
	global_load_dword v22, v[30:31], off
	global_load_dword v23, v[34:35], off
	v_add_u32_e32 v26, 32, v32
	v_ashrrev_i32_e32 v27, 31, v26
	v_mul_lo_u32 v28, s8, v27
	v_mul_lo_u32 v29, s9, v26
	v_mad_u64_u32 v[26:27], s[6:7], s8, v26, 0
	v_add3_u32 v27, v27, v28, v29
	v_add_u32_e32 v28, 36, v32
	v_ashrrev_i32_e32 v29, 31, v28
	v_mul_lo_u32 v30, s8, v29
	v_mul_lo_u32 v31, s9, v28
	v_mad_u64_u32 v[28:29], s[6:7], s8, v28, 0
	v_add3_u32 v29, v29, v30, v31
	v_add_u32_e32 v30, 40, v32
	v_ashrrev_i32_e32 v31, 31, v30
	v_mul_lo_u32 v34, s8, v31
	v_mul_lo_u32 v35, s9, v30
	v_mad_u64_u32 v[30:31], s[6:7], s8, v30, 0
	v_add3_u32 v31, v31, v34, v35
	v_add_u32_e32 v34, 44, v32
	v_ashrrev_i32_e32 v35, 31, v34
	v_mul_lo_u32 v36, s8, v35
	v_mul_lo_u32 v37, s9, v34
	v_mad_u64_u32 v[34:35], s[6:7], s8, v34, 0
	v_add3_u32 v35, v35, v36, v37
	v_add_u32_e32 v36, 48, v32
	v_ashrrev_i32_e32 v37, 31, v36
	v_mul_lo_u32 v38, s8, v37
	v_mul_lo_u32 v39, s9, v36
	v_mad_u64_u32 v[36:37], s[6:7], s8, v36, 0
	v_add3_u32 v37, v37, v38, v39
	v_add_u32_e32 v38, 52, v32
	v_ashrrev_i32_e32 v39, 31, v38
	v_mul_lo_u32 v40, s8, v39
	v_mul_lo_u32 v41, s9, v38
	v_mad_u64_u32 v[38:39], s[6:7], s8, v38, 0
	v_add3_u32 v39, v39, v40, v41
	v_add_u32_e32 v40, 56, v32
	v_ashrrev_i32_e32 v41, 31, v40
	v_mul_lo_u32 v42, s8, v41
	v_mul_lo_u32 v43, s9, v40
	v_mad_u64_u32 v[40:41], s[6:7], s8, v40, 0
	v_add_u32_e32 v32, 60, v32
	v_add3_u32 v41, v41, v42, v43
	v_ashrrev_i32_e32 v42, 31, v32
	v_mul_lo_u32 v44, s8, v42
	v_mul_lo_u32 v45, s9, v32
	v_mad_u64_u32 v[42:43], s[6:7], s8, v32, 0
	v_lshl_add_u64 v[26:27], v[26:27], 2, v[24:25]
	v_lshl_add_u64 v[28:29], v[28:29], 2, v[24:25]
	v_lshl_add_u64 v[30:31], v[30:31], 2, v[24:25]
	v_add3_u32 v43, v43, v44, v45
	v_lshl_add_u64 v[34:35], v[34:35], 2, v[24:25]
	v_lshl_add_u64 v[36:37], v[36:37], 2, v[24:25]
	v_lshl_add_u64 v[38:39], v[38:39], 2, v[24:25]
	v_lshl_add_u64 v[40:41], v[40:41], 2, v[24:25]
	v_lshl_add_u64 v[42:43], v[42:43], 2, v[24:25]
	global_load_dword v24, v[26:27], off
	global_load_dword v25, v[28:29], off
	s_nop 0
	global_load_dword v26, v[30:31], off
	global_load_dword v27, v[34:35], off
	global_load_dword v28, v[36:37], off
	global_load_dword v29, v[38:39], off
	s_nop 0
	global_load_dword v30, v[40:41], off
	global_load_dword v31, v[42:43], off
; DEV int tid_opaque() { int t = threadIdx.x; asm volatile("" : "+v"(t)); return t; }
; DEV unsigned pk_bf16(float lo, float hi) { const f32x2_t f = {lo, hi}; const bf16x2_t b = __builtin_convertvector(f, bf16x2_t); return __builtin_bit_cast(unsigned, b); }
; DEV void wt_store(const WtDesc& d, const float (&r)[16], float* sm) {
;     const int t = tid_opaque(), c = t & 63, r0 = t >> 6;
; #pragma unroll
;     for (int i = 0; i < 16; ++i) sm[(r0 + 4 * i) * 65 + c] = r[i];
;     __syncthreads();
;     const int n = t >> 2, kc = (t & 3) * 16;
;     unsigned w[8];
; #pragma unroll
;     for (int e = 0; e < 8; ++e) w[e] = pk_bf16(sm[(kc + 2 * e) * 65 + n], sm[(kc + 2 * e + 1) * 65 + n]);
;     uint4* o = (uint4*)(d.dst + (size_t)n * d.ldd + kc);
;     o[0] = make_uint4(w[0], w[1], w[2], w[3]);
;     o[1] = make_uint4(w[4], w[5], w[6], w[7]);
;     __syncthreads();
; }
; DEV void wt_all(const Params& p, int bid, int nb, float* sm) {
;     ...
;         wt_store(d, r, sm);
;         if (!more) break;
;         d = dn; job = nj;
; #pragma unroll
;         for (int i = 0; i < 16; ++i) r[i] = rn[i];
.LBB0_2676:
	v_mov_b32_e32 v32, v186
	v_readlane_b32 s6, v254, 4
	v_and_b32_e32 v34, 63, v32
	v_ashrrev_i32_e32 v35, 6, v32
	v_lshlrev_b32_e32 v34, 2, v34
	v_mul_lo_u32 v35, v35, s4
	v_add3_u32 v34, 0, v34, v35
	s_waitcnt vmcnt(16)
	ds_write_b32 v34, v0
	ds_write_b32 v34, v1 offset:1040
	ds_write_b32 v34, v2 offset:2080
	ds_write_b32 v34, v3 offset:3120
	ds_write_b32 v34, v4 offset:4160
	ds_write_b32 v34, v5 offset:5200
	ds_write_b32 v34, v6 offset:6240
	ds_write_b32 v34, v7 offset:7280
	ds_write_b32 v34, v8 offset:8320
	ds_write_b32 v34, v9 offset:9360
	ds_write_b32 v34, v10 offset:10400
	ds_write_b32 v34, v11 offset:11440
	ds_write_b32 v34, v12 offset:12480
	ds_write_b32 v34, v13 offset:13520
	ds_write_b32 v34, v14 offset:14560
	ds_write_b32 v34, v15 offset:15600
	v_lshlrev_b32_e32 v0, 4, v32
	v_and_b32_e32 v14, 48, v0
	v_mul_u32_u24_e32 v0, 0x41, v14
	v_and_b32_e32 v2, -4, v32
	v_lshlrev_b32_e32 v3, 2, v0
	v_add3_u32 v10, 0, v2, v3
	v_add3_u32 v12, 0, v3, v2
	s_waitcnt lgkmcnt(0)
	s_barrier
	ds_read2_b32 v[0:1], v10 offset1:130
	ds_read2_b32 v[2:3], v12 offset0:65 offset1:195
	v_add_u32_e32 v4, 0x400, v12
	v_add_u32_e32 v6, 0x800, v10
	v_add_u32_e32 v8, 0x800, v12
	ds_read2_b32 v[4:5], v4 offset0:69 offset1:199
	s_waitcnt lgkmcnt(1)
	v_cvt_pk_bf16_f32 v0, v0, v2
	v_add_u32_e32 v2, 0x400, v10
	v_cvt_pk_bf16_f32 v1, v1, v3
	ds_read2_b32 v[2:3], v2 offset0:4 offset1:134
	ds_read2_b32 v[6:7], v6 offset0:8 offset1:138
	ds_read2_b32 v[8:9], v8 offset0:73 offset1:203
	v_add_u32_e32 v10, 0xc00, v10
	v_add_u32_e32 v12, 0xc00, v12
	ds_read2_b32 v[10:11], v10 offset0:12 offset1:142
	ds_read2_b32 v[12:13], v12 offset0:77 offset1:207
	v_readlane_b32 s7, v254, 5
	v_ashrrev_i32_e32 v15, 2, v32
	s_mov_b32 s8, s6
	s_add_i32 s30, s30, s6
	s_waitcnt lgkmcnt(4)
	v_cvt_pk_bf16_f32 v2, v2, v4
	v_cvt_pk_bf16_f32 v3, v3, v5
	s_waitcnt lgkmcnt(2)
	v_cvt_pk_bf16_f32 v4, v6, v8
	v_cvt_pk_bf16_f32 v5, v7, v9
	v_mad_u64_u32 v[8:9], s[6:7], v15, s12, 0
	s_waitcnt lgkmcnt(0)
	v_cvt_pk_bf16_f32 v6, v10, v12
	v_cvt_pk_bf16_f32 v7, v11, v13
	v_ashrrev_i32_e32 v11, 31, v15
	v_mov_b32_e32 v10, v9
	v_mad_u64_u32 v[10:11], s[6:7], v11, s12, v[10:11]
	v_mov_b32_e32 v9, v10
	v_lshl_add_u64 v[8:9], v[8:9], 1, s[0:1]
	v_lshlrev_b32_e32 v32, 1, v14
	v_lshl_add_u64 v[8:9], v[8:9], 0, v[32:33]
	s_add_i32 s29, s29, s8
	s_bitcmp1_b32 s0, 0
	s_cbranch_scc0 .Lwt_lin
	s_and_b32 s0, s0, -2
	s_lshl_b32 s6, s12, 2
	v_lshrrev_b32_e32 v10, 3, v186
	v_mul_u32_u24_e32 v10, s6, v10
	v_and_b32_e32 v11, 2, v186
	v_lshl_or_b32 v10, v11, 6, v10
	v_and_b32_e32 v11, 4, v186
	v_lshl_or_b32 v10, v11, 4, v10
	v_and_b32_e32 v11, 1, v186
	v_lshl_or_b32 v10, v11, 5, v10
	v_mov_b32_e32 v11, 0
	v_lshl_add_u64 v[8:9], s[0:1], 0, v[10:11]
.Lwt_lin:
	global_store_dwordx4 v[8:9], v[0:3], off
	global_store_dwordx4 v[8:9], v[4:7], off offset:16
	s_cmpk_gt_i32 s30, 0x1fbf
	s_mov_b32 s12, s5
	s_mov_b64 s[0:1], s[2:3]
	s_waitcnt vmcnt(2)
	v_mov_b32_e32 v0, v16
	v_mov_b32_e32 v1, v17
	v_mov_b32_e32 v2, v18
	v_mov_b32_e32 v3, v19
	v_mov_b32_e32 v4, v20
	v_mov_b32_e32 v5, v21
	v_mov_b32_e32 v6, v22
	v_mov_b32_e32 v7, v23
	v_mov_b32_e32 v8, v24
	v_mov_b32_e32 v9, v25
	v_mov_b32_e32 v10, v26
	v_mov_b32_e32 v11, v27
	v_mov_b32_e32 v12, v28
	v_mov_b32_e32 v13, v29
	v_mov_b32_e32 v14, v30
	v_mov_b32_e32 v15, v31
	s_waitcnt lgkmcnt(0)
	s_barrier
	s_cbranch_scc1 .LBB0_2706
